# early acquire invalidate also in the phase-0 barrier copy
# baseline (speedup 1.0000x reference)
.LBB0_107:
	s_or_b64 exec, exec, s[6:7]
	v_cvt_f32_u32_e32 v4, v2
	s_waitcnt vmcnt(0)
	buffer_inv sc1
	v_readfirstlane_b32 s4, v3
	v_sub_u32_e32 v3, 0, v2
	v_rcp_iflag_f32_e32 v4, v4
	v_add_u32_e32 v5, s4, v1
	v_mul_f32_e32 v4, 0x4f7ffffe, v4
	v_cvt_u32_f32_e32 v4, v4
	v_mul_lo_u32 v1, v3, v4
	v_mul_hi_u32 v1, v4, v1
	v_add_u32_e32 v1, v4, v1
	v_mul_hi_u32 v1, v5, v1
	v_mul_lo_u32 v3, v1, v2
	v_sub_u32_e32 v3, v5, v3
	v_add_u32_e32 v4, 1, v1
	v_cmp_ge_u32_e32 vcc, v3, v2
	s_nop 1
	v_cndmask_b32_e32 v1, v1, v4, vcc
	v_sub_u32_e32 v4, v3, v2
	v_cndmask_b32_e32 v3, v3, v4, vcc
	v_add_u32_e32 v4, 1, v1
	v_cmp_ge_u32_e32 vcc, v3, v2
	v_add_u32_e32 v3, 1, v5
	s_nop 0
	v_cndmask_b32_e32 v1, v1, v4, vcc
	v_mul_lo_u32 v4, v2, v1
	v_add_u32_e32 v2, v4, v2
	v_cmp_ne_u32_e32 vcc, v3, v2
	s_and_saveexec_b64 s[4:5], vcc
	s_xor_b64 s[4:5], exec, s[4:5]
	s_cbranch_execz .LBB0_121
	s_waitcnt lgkmcnt(0)
	v_mov_b32_e32 v0, 0x2000
	global_load_dword v0, v0, s[2:3] offset:1024 sc1
	s_add_u32 s10, s2, 0x2400
	s_addc_u32 s11, s3, 0
	s_waitcnt vmcnt(0)
	v_cmp_eq_u32_e32 vcc, v0, v1
	s_and_saveexec_b64 s[6:7], vcc
	s_cbranch_execz .LBB0_120
	s_add_u32 s8, s42, 0xc0200
	s_addc_u32 s9, s43, 0
	s_mov_b32 s22, 1
	s_mov_b64 s[12:13], 0
	v_mov_b32_e32 v0, 0
	s_branch .LBB0_111

.LBB0_120:
	s_or_b64 exec, exec, s[6:7]
	s_waitcnt vmcnt(0)
	s_waitcnt vmcnt(0)

.LBB0_138:
	s_or_b64 exec, exec, s[4:5]
	s_mov_b64 s[4:5], exec
	v_mbcnt_lo_u32_b32 v0, s4, 0
	v_mbcnt_hi_u32_b32 v0, s5, v0
	v_cmp_eq_u32_e32 vcc, 0, v0
	s_waitcnt vmcnt(0)
	s_and_saveexec_b64 s[6:7], vcc
	s_cbranch_execz .LBB0_140
	s_bcnt1_i32_b64 s4, s[4:5]
	v_mov_b32_e32 v0, 0x2000
	v_mov_b32_e32 v1, s4
	global_atomic_add v0, v1, s[2:3] offset:1024
